# v21: v20 + removed 316 compiler-inserted s_nop 0 between the top-k count-loop cmp/addc inline-asm pairs (no hazard between them)
# speedup vs baseline: 1.0068x; 1.0009x over previous
; template <int NV>
; DI void topk_row(const float* row, int s, LAS int* lst, int lane) {
;     ...
; #pragma unroll 1
;     ...
;         const unsigned cand = T | (1u << bit); int c = 0;
; #pragma unroll
;         for (int j = 0; j < NV; ++j) asm volatile("v_cmp_le_u32 vcc, %2, %1\n\tv_addc_co_u32 %0, vcc, 0, %0, vcc" : "+v"(c) : "v"(key[j]), "s"(cand) : "vcc");
;         const int tot = wave_sum_i(c);
;         if (tot >= 256) T = cand;
;         if (tot == 256) break;
;     }
.LBB0_1969:
	v_lshlrev_b32_e64 v54, v53, 1
	v_mov_b32_e32 v55, 0
	v_or_b32_e32 v54, v54, v34
	v_cmp_le_u32 vcc, v54, v141
	v_addc_co_u32 v55, vcc, 0, v55, vcc
	v_cmp_le_u32 vcc, v54, v140
	v_addc_co_u32 v55, vcc, 0, v55, vcc
	v_cmp_le_u32 vcc, v54, v139
	v_addc_co_u32 v55, vcc, 0, v55, vcc
	v_cmp_le_u32 vcc, v54, v138
	v_addc_co_u32 v55, vcc, 0, v55, vcc
	v_cmp_le_u32 vcc, v54, v137
	v_addc_co_u32 v55, vcc, 0, v55, vcc
	v_cmp_le_u32 vcc, v54, v136
	v_addc_co_u32 v55, vcc, 0, v55, vcc
	v_cmp_le_u32 vcc, v54, v135
	v_addc_co_u32 v55, vcc, 0, v55, vcc
	v_cmp_le_u32 vcc, v54, v134
	v_addc_co_u32 v55, vcc, 0, v55, vcc
	v_cmp_le_u32 vcc, v54, v133
	v_addc_co_u32 v55, vcc, 0, v55, vcc
	v_cmp_le_u32 vcc, v54, v132
	v_addc_co_u32 v55, vcc, 0, v55, vcc
	v_cmp_le_u32 vcc, v54, v251
	v_addc_co_u32 v55, vcc, 0, v55, vcc
	v_cmp_le_u32 vcc, v54, v248
	v_addc_co_u32 v55, vcc, 0, v55, vcc
	v_cmp_le_u32 vcc, v54, v247
	v_addc_co_u32 v55, vcc, 0, v55, vcc
	v_cmp_le_u32 vcc, v54, v253
	v_addc_co_u32 v55, vcc, 0, v55, vcc
	v_cmp_le_u32 vcc, v54, v249
	v_addc_co_u32 v55, vcc, 0, v55, vcc
	v_cmp_le_u32 vcc, v54, v252
	v_addc_co_u32 v55, vcc, 0, v55, vcc
	v_cmp_le_u32 vcc, v54, v128
	v_addc_co_u32 v55, vcc, 0, v55, vcc
	v_cmp_le_u32 vcc, v54, v130
	v_addc_co_u32 v55, vcc, 0, v55, vcc
	v_cmp_le_u32 vcc, v54, v131
	v_addc_co_u32 v55, vcc, 0, v55, vcc
	v_cmp_le_u32 vcc, v54, v129
	v_addc_co_u32 v55, vcc, 0, v55, vcc
	v_cmp_le_u32 vcc, v54, v250
	v_addc_co_u32 v55, vcc, 0, v55, vcc
	v_cmp_le_u32 vcc, v54, v246
	v_addc_co_u32 v55, vcc, 0, v55, vcc
	v_cmp_le_u32 vcc, v54, v245
	v_addc_co_u32 v55, vcc, 0, v55, vcc
	v_cmp_le_u32 vcc, v54, v244
	v_addc_co_u32 v55, vcc, 0, v55, vcc
	v_cmp_le_u32 vcc, v54, v243
	v_addc_co_u32 v55, vcc, 0, v55, vcc
	v_cmp_le_u32 vcc, v54, v242
	v_addc_co_u32 v55, vcc, 0, v55, vcc
	v_cmp_le_u32 vcc, v54, v241
	v_addc_co_u32 v55, vcc, 0, v55, vcc
	v_cmp_le_u32 vcc, v54, v240
	v_addc_co_u32 v55, vcc, 0, v55, vcc
	v_cmp_le_u32 vcc, v54, v239
	v_addc_co_u32 v55, vcc, 0, v55, vcc
	v_cmp_le_u32 vcc, v54, v238
	v_addc_co_u32 v55, vcc, 0, v55, vcc
	v_cmp_le_u32 vcc, v54, v237
	v_addc_co_u32 v55, vcc, 0, v55, vcc
	v_cmp_le_u32 vcc, v54, v236
	v_addc_co_u32 v55, vcc, 0, v55, vcc
	v_cmp_le_u32 vcc, v54, v235
	v_addc_co_u32 v55, vcc, 0, v55, vcc
	v_cmp_le_u32 vcc, v54, v234
	v_addc_co_u32 v55, vcc, 0, v55, vcc
	v_cmp_le_u32 vcc, v54, v233
	v_addc_co_u32 v55, vcc, 0, v55, vcc
	v_cmp_le_u32 vcc, v54, v232
	v_addc_co_u32 v55, vcc, 0, v55, vcc
	v_cmp_le_u32 vcc, v54, v231
	v_addc_co_u32 v55, vcc, 0, v55, vcc
	v_cmp_le_u32 vcc, v54, v230
	v_addc_co_u32 v55, vcc, 0, v55, vcc
	v_cmp_le_u32 vcc, v54, v229
	v_addc_co_u32 v55, vcc, 0, v55, vcc
	v_cmp_le_u32 vcc, v54, v228
	v_addc_co_u32 v55, vcc, 0, v55, vcc
	v_cmp_le_u32 vcc, v54, v227
	v_addc_co_u32 v55, vcc, 0, v55, vcc
	v_cmp_le_u32 vcc, v54, v226
	v_addc_co_u32 v55, vcc, 0, v55, vcc
	v_cmp_le_u32 vcc, v54, v225
	v_addc_co_u32 v55, vcc, 0, v55, vcc
	v_cmp_le_u32 vcc, v54, v224
	v_addc_co_u32 v55, vcc, 0, v55, vcc
	v_cmp_le_u32 vcc, v54, v223
	v_addc_co_u32 v55, vcc, 0, v55, vcc
	v_cmp_le_u32 vcc, v54, v222
	v_addc_co_u32 v55, vcc, 0, v55, vcc
	v_cmp_le_u32 vcc, v54, v221
	v_addc_co_u32 v55, vcc, 0, v55, vcc
	v_cmp_le_u32 vcc, v54, v220
	v_addc_co_u32 v55, vcc, 0, v55, vcc
	v_cmp_le_u32 vcc, v54, v219
	v_addc_co_u32 v55, vcc, 0, v55, vcc
	v_cmp_le_u32 vcc, v54, v218
	v_addc_co_u32 v55, vcc, 0, v55, vcc
	v_cmp_le_u32 vcc, v54, v217
	v_addc_co_u32 v55, vcc, 0, v55, vcc
	v_cmp_le_u32 vcc, v54, v216
	v_addc_co_u32 v55, vcc, 0, v55, vcc
	v_cmp_le_u32 vcc, v54, v215
	v_addc_co_u32 v55, vcc, 0, v55, vcc
	v_cmp_le_u32 vcc, v54, v214
	v_addc_co_u32 v55, vcc, 0, v55, vcc
	v_cmp_le_u32 vcc, v54, v213
	v_addc_co_u32 v55, vcc, 0, v55, vcc
	v_cmp_le_u32 vcc, v54, v212
	v_addc_co_u32 v55, vcc, 0, v55, vcc
	v_cmp_le_u32 vcc, v54, v211
	v_addc_co_u32 v55, vcc, 0, v55, vcc
	v_cmp_le_u32 vcc, v54, v210
	v_addc_co_u32 v55, vcc, 0, v55, vcc
	v_cmp_le_u32 vcc, v54, v209
	v_addc_co_u32 v55, vcc, 0, v55, vcc
	v_cmp_le_u32 vcc, v54, v208
	v_addc_co_u32 v55, vcc, 0, v55, vcc
	v_cmp_le_u32 vcc, v54, v207
	v_addc_co_u32 v55, vcc, 0, v55, vcc
	v_cmp_le_u32 vcc, v54, v206
	v_addc_co_u32 v55, vcc, 0, v55, vcc
	v_cmp_le_u32 vcc, v54, v205
	v_addc_co_u32 v55, vcc, 0, v55, vcc
	v_cmp_le_u32 vcc, v54, v204
	v_addc_co_u32 v55, vcc, 0, v55, vcc
	v_cmp_le_u32 vcc, v54, v203
	v_addc_co_u32 v55, vcc, 0, v55, vcc
	v_cmp_le_u32 vcc, v54, v202
	v_addc_co_u32 v55, vcc, 0, v55, vcc
	v_cmp_le_u32 vcc, v54, v201
	v_addc_co_u32 v55, vcc, 0, v55, vcc
	v_cmp_le_u32 vcc, v54, v200
	v_addc_co_u32 v55, vcc, 0, v55, vcc
	v_cmp_le_u32 vcc, v54, v199
	v_addc_co_u32 v55, vcc, 0, v55, vcc
	v_cmp_le_u32 vcc, v54, v198
	v_addc_co_u32 v55, vcc, 0, v55, vcc
	v_cmp_le_u32 vcc, v54, v197
	v_addc_co_u32 v55, vcc, 0, v55, vcc
	v_cmp_le_u32 vcc, v54, v196
	v_addc_co_u32 v55, vcc, 0, v55, vcc
	v_cmp_le_u32 vcc, v54, v195
	v_addc_co_u32 v55, vcc, 0, v55, vcc
	v_cmp_le_u32 vcc, v54, v194
; DI unsigned mbcnt64(unsigned long long m) { return __builtin_amdgcn_mbcnt_hi((unsigned)(m >> 32), __builtin_amdgcn_mbcnt_lo((unsigned)m, 0u)); }
; template <int NV>
; DI void topk_row(const float* row, int s, LAS int* lst, int lane) {
;     ...
; #pragma unroll 1
;     ...
;         const unsigned cand = T | (1u << bit); int c = 0;
; #pragma unroll
;         for (int j = 0; j < NV; ++j) asm volatile("v_cmp_le_u32 vcc, %2, %1\n\tv_addc_co_u32 %0, vcc, 0, %0, vcc" : "+v"(c) : "v"(key[j]), "s"(cand) : "vcc");
;         const int tot = wave_sum_i(c);
;         if (tot >= 256) T = cand;
;         if (tot == 256) break;
;     }
;     int bgt = 0;
; #pragma unroll
;     for (int j = 0; j < NV; ++j) { const bool sg = key[j] > T; const unsigned long long mg = __ballot(sg); if (sg) lst[bgt + (int)mbcnt64(mg)] = j * 64 + lane; bgt += __builtin_popcountll(mg); }
	v_addc_co_u32 v55, vcc, 0, v55, vcc
	v_cmp_le_u32 vcc, v54, v193
	v_addc_co_u32 v55, vcc, 0, v55, vcc
	v_cmp_le_u32 vcc, v54, v192
	v_addc_co_u32 v55, vcc, 0, v55, vcc
	v_cmp_le_u32 vcc, v54, v191
	v_addc_co_u32 v55, vcc, 0, v55, vcc
	v_cmp_le_u32 vcc, v54, v190
	v_addc_co_u32 v55, vcc, 0, v55, vcc
	v_cmp_le_u32 vcc, v54, v189
	v_addc_co_u32 v55, vcc, 0, v55, vcc
	v_cmp_le_u32 vcc, v54, v187
	v_addc_co_u32 v55, vcc, 0, v55, vcc
	v_cmp_le_u32 vcc, v54, v188
	v_addc_co_u32 v55, vcc, 0, v55, vcc
	v_cmp_le_u32 vcc, v54, v186
	v_addc_co_u32 v55, vcc, 0, v55, vcc
	v_cmp_le_u32 vcc, v54, v185
	v_addc_co_u32 v55, vcc, 0, v55, vcc
	v_cmp_le_u32 vcc, v54, v184
	v_addc_co_u32 v55, vcc, 0, v55, vcc
	v_cmp_le_u32 vcc, v54, v183
	v_addc_co_u32 v55, vcc, 0, v55, vcc
	v_cmp_le_u32 vcc, v54, v182
	v_addc_co_u32 v55, vcc, 0, v55, vcc
	v_cmp_le_u32 vcc, v54, v181
	v_addc_co_u32 v55, vcc, 0, v55, vcc
	v_cmp_le_u32 vcc, v54, v180
	v_addc_co_u32 v55, vcc, 0, v55, vcc
	v_cmp_le_u32 vcc, v54, v179
	v_addc_co_u32 v55, vcc, 0, v55, vcc
	v_cmp_le_u32 vcc, v54, v178
	v_addc_co_u32 v55, vcc, 0, v55, vcc
	v_cmp_le_u32 vcc, v54, v177
	v_addc_co_u32 v55, vcc, 0, v55, vcc
	v_cmp_le_u32 vcc, v54, v176
	v_addc_co_u32 v55, vcc, 0, v55, vcc
	v_cmp_le_u32 vcc, v54, v175
	v_addc_co_u32 v55, vcc, 0, v55, vcc
	v_cmp_le_u32 vcc, v54, v174
	v_addc_co_u32 v55, vcc, 0, v55, vcc
	v_cmp_le_u32 vcc, v54, v173
	v_addc_co_u32 v55, vcc, 0, v55, vcc
	v_cmp_le_u32 vcc, v54, v172
	v_addc_co_u32 v55, vcc, 0, v55, vcc
	v_cmp_le_u32 vcc, v54, v171
	v_addc_co_u32 v55, vcc, 0, v55, vcc
	v_cmp_le_u32 vcc, v54, v170
	v_addc_co_u32 v55, vcc, 0, v55, vcc
	v_cmp_le_u32 vcc, v54, v169
	v_addc_co_u32 v55, vcc, 0, v55, vcc
	v_cmp_le_u32 vcc, v54, v168
	v_addc_co_u32 v55, vcc, 0, v55, vcc
	v_cmp_le_u32 vcc, v54, v166
	v_addc_co_u32 v55, vcc, 0, v55, vcc
	v_cmp_le_u32 vcc, v54, v164
	v_addc_co_u32 v55, vcc, 0, v55, vcc
	v_cmp_le_u32 vcc, v54, v167
	v_addc_co_u32 v55, vcc, 0, v55, vcc
	v_cmp_le_u32 vcc, v54, v165
	v_addc_co_u32 v55, vcc, 0, v55, vcc
	v_cmp_le_u32 vcc, v54, v162
	v_addc_co_u32 v55, vcc, 0, v55, vcc
	v_cmp_le_u32 vcc, v54, v163
	v_addc_co_u32 v55, vcc, 0, v55, vcc
	v_cmp_le_u32 vcc, v54, v62
	v_addc_co_u32 v55, vcc, 0, v55, vcc
	v_cmp_le_u32 vcc, v54, v58
	v_addc_co_u32 v55, vcc, 0, v55, vcc
	v_cmp_le_u32 vcc, v54, v56
	v_addc_co_u32 v55, vcc, 0, v55, vcc
	v_cmp_le_u32 vcc, v54, v52
	v_addc_co_u32 v55, vcc, 0, v55, vcc
	v_cmp_le_u32 vcc, v54, v50
	v_addc_co_u32 v55, vcc, 0, v55, vcc
	v_cmp_le_u32 vcc, v54, v49
	v_addc_co_u32 v55, vcc, 0, v55, vcc
	v_cmp_le_u32 vcc, v54, v48
	v_addc_co_u32 v55, vcc, 0, v55, vcc
	v_cmp_le_u32 vcc, v54, v51
	v_addc_co_u32 v55, vcc, 0, v55, vcc
	v_cmp_le_u32 vcc, v54, v47
	v_addc_co_u32 v55, vcc, 0, v55, vcc
	v_cmp_le_u32 vcc, v54, v46
	v_addc_co_u32 v55, vcc, 0, v55, vcc
	v_cmp_le_u32 vcc, v54, v45
	v_addc_co_u32 v55, vcc, 0, v55, vcc
	v_cmp_le_u32 vcc, v54, v44
	v_addc_co_u32 v55, vcc, 0, v55, vcc
	v_cmp_le_u32 vcc, v54, v43
	v_addc_co_u32 v55, vcc, 0, v55, vcc
	v_cmp_le_u32 vcc, v54, v42
	v_addc_co_u32 v55, vcc, 0, v55, vcc
	v_cmp_le_u32 vcc, v54, v41
	v_addc_co_u32 v55, vcc, 0, v55, vcc
	v_cmp_le_u32 vcc, v54, v40
	v_addc_co_u32 v55, vcc, 0, v55, vcc
	v_cmp_le_u32 vcc, v54, v39
	v_addc_co_u32 v55, vcc, 0, v55, vcc
	v_cmp_le_u32 vcc, v54, v38
	v_addc_co_u32 v55, vcc, 0, v55, vcc
	v_cmp_le_u32 vcc, v54, v37
	v_addc_co_u32 v55, vcc, 0, v55, vcc
	v_cmp_le_u32 vcc, v54, v36
	v_addc_co_u32 v55, vcc, 0, v55, vcc
	v_cmp_le_u32 vcc, v54, v35
	v_addc_co_u32 v55, vcc, 0, v55, vcc
	v_cmp_le_u32 vcc, v54, v0
	v_addc_co_u32 v55, vcc, 0, v55, vcc
	s_nop 1
	v_add_u32_dpp v55, v55, v55 quad_perm:[1,0,3,2] row_mask:0xf bank_mask:0xf bound_ctrl:1
	s_nop 1
	v_add_u32_dpp v55, v55, v55 quad_perm:[2,3,0,1] row_mask:0xf bank_mask:0xf bound_ctrl:1
	s_nop 1
	v_add_u32_dpp v55, v55, v55 row_half_mirror row_mask:0xf bank_mask:0xf bound_ctrl:1
	s_nop 1
	v_add_u32_dpp v55, v55, v55 row_mirror row_mask:0xf bank_mask:0xf bound_ctrl:1
	s_nop 0
	v_readlane_b32 s0, v55, 0
	v_readlane_b32 s1, v55, 16
	s_add_i32 s0, s1, s0
	v_readlane_b32 s1, v55, 32
	s_add_i32 s0, s0, s1
	v_readlane_b32 s1, v55, 48
	s_add_i32 s0, s0, s1
	s_cmpk_gt_i32 s0, 0xff
	s_cselect_b64 vcc, -1, 0
	s_cmpk_eq_i32 s0, 0x100
	v_cndmask_b32_e32 v34, v34, v54, vcc
	s_cselect_b64 s[0:1], -1, 0
	v_subrev_co_u32_e32 v53, vcc, 1, v53
	s_or_b64 s[0:1], s[0:1], vcc
	s_andn2_b64 vcc, exec, s[0:1]
	s_cbranch_vccnz .LBB0_1969
	v_cmp_gt_u32_e32 vcc, v141, v34
	s_and_saveexec_b64 s[0:1], vcc
	s_nop 0
	v_mbcnt_lo_u32_b32 v53, vcc_lo, 0
	v_mbcnt_hi_u32_b32 v53, vcc_hi, v53
	v_lshl_add_u32 v53, v53, 2, s20
	ds_write_b32 v53, v2
	s_or_b64 exec, exec, s[0:1]
	s_bcnt1_i32_b64 s2, vcc
	v_cmp_gt_u32_e32 vcc, v140, v34
	s_and_saveexec_b64 s[0:1], vcc
	s_cbranch_execz .LBB0_1974
	s_lshl_b32 s3, s2, 2
	v_mbcnt_lo_u32_b32 v53, vcc_lo, 0
	s_add_i32 s3, s20, s3
	v_mbcnt_hi_u32_b32 v53, vcc_hi, v53
	v_lshl_add_u32 v53, v53, 2, s3
	ds_write_b32 v53, v4

; template <int NV>
; DI void topk_row(const float* row, int s, LAS int* lst, int lane) {
;     ...
; #pragma unroll 1
;     ...
;         const unsigned cand = T | (1u << bit); int c = 0;
; #pragma unroll
;         for (int j = 0; j < NV; ++j) asm volatile("v_cmp_le_u32 vcc, %2, %1\n\tv_addc_co_u32 %0, vcc, 0, %0, vcc" : "+v"(c) : "v"(key[j]), "s"(cand) : "vcc");
;         const int tot = wave_sum_i(c);
;         if (tot >= 256) T = cand;
;         if (tot == 256) break;
;     }
.LBB0_2485:
	v_lshlrev_b32_e64 v54, v53, 1
	v_mov_b32_e32 v55, 0
	v_or_b32_e32 v54, v54, v34
	v_cmp_le_u32 vcc, v54, v221
	v_addc_co_u32 v55, vcc, 0, v55, vcc
	v_cmp_le_u32 vcc, v54, v220
	v_addc_co_u32 v55, vcc, 0, v55, vcc
	v_cmp_le_u32 vcc, v54, v219
	v_addc_co_u32 v55, vcc, 0, v55, vcc
	v_cmp_le_u32 vcc, v54, v218
	v_addc_co_u32 v55, vcc, 0, v55, vcc
	v_cmp_le_u32 vcc, v54, v217
	v_addc_co_u32 v55, vcc, 0, v55, vcc
	v_cmp_le_u32 vcc, v54, v216
	v_addc_co_u32 v55, vcc, 0, v55, vcc
	v_cmp_le_u32 vcc, v54, v215
	v_addc_co_u32 v55, vcc, 0, v55, vcc
	v_cmp_le_u32 vcc, v54, v214
	v_addc_co_u32 v55, vcc, 0, v55, vcc
	v_cmp_le_u32 vcc, v54, v213
	v_addc_co_u32 v55, vcc, 0, v55, vcc
	v_cmp_le_u32 vcc, v54, v211
	v_addc_co_u32 v55, vcc, 0, v55, vcc
	v_cmp_le_u32 vcc, v54, v206
	v_addc_co_u32 v55, vcc, 0, v55, vcc
	v_cmp_le_u32 vcc, v54, v203
	v_addc_co_u32 v55, vcc, 0, v55, vcc
	v_cmp_le_u32 vcc, v54, v200
	v_addc_co_u32 v55, vcc, 0, v55, vcc
	v_cmp_le_u32 vcc, v54, v202
	v_addc_co_u32 v55, vcc, 0, v55, vcc
	v_cmp_le_u32 vcc, v54, v204
	v_addc_co_u32 v55, vcc, 0, v55, vcc
	v_cmp_le_u32 vcc, v54, v207
	v_addc_co_u32 v55, vcc, 0, v55, vcc
	v_cmp_le_u32 vcc, v54, v208
	v_addc_co_u32 v55, vcc, 0, v55, vcc
	v_cmp_le_u32 vcc, v54, v212
	v_addc_co_u32 v55, vcc, 0, v55, vcc
	v_cmp_le_u32 vcc, v54, v210
	v_addc_co_u32 v55, vcc, 0, v55, vcc
	v_cmp_le_u32 vcc, v54, v209
	v_addc_co_u32 v55, vcc, 0, v55, vcc
	v_cmp_le_u32 vcc, v54, v205
	v_addc_co_u32 v55, vcc, 0, v55, vcc
	v_cmp_le_u32 vcc, v54, v201
	v_addc_co_u32 v55, vcc, 0, v55, vcc
	v_cmp_le_u32 vcc, v54, v199
	v_addc_co_u32 v55, vcc, 0, v55, vcc
	v_cmp_le_u32 vcc, v54, v198
	v_addc_co_u32 v55, vcc, 0, v55, vcc
	v_cmp_le_u32 vcc, v54, v197
	v_addc_co_u32 v55, vcc, 0, v55, vcc
	v_cmp_le_u32 vcc, v54, v196
	v_addc_co_u32 v55, vcc, 0, v55, vcc
	v_cmp_le_u32 vcc, v54, v195
	v_addc_co_u32 v55, vcc, 0, v55, vcc
	v_cmp_le_u32 vcc, v54, v194
	v_addc_co_u32 v55, vcc, 0, v55, vcc
	v_cmp_le_u32 vcc, v54, v193
	v_addc_co_u32 v55, vcc, 0, v55, vcc
	v_cmp_le_u32 vcc, v54, v192
	v_addc_co_u32 v55, vcc, 0, v55, vcc
	v_cmp_le_u32 vcc, v54, v191
	v_addc_co_u32 v55, vcc, 0, v55, vcc
	v_cmp_le_u32 vcc, v54, v190
	v_addc_co_u32 v55, vcc, 0, v55, vcc
	v_cmp_le_u32 vcc, v54, v189
	v_addc_co_u32 v55, vcc, 0, v55, vcc
	v_cmp_le_u32 vcc, v54, v188
	v_addc_co_u32 v55, vcc, 0, v55, vcc
	v_cmp_le_u32 vcc, v54, v187
	v_addc_co_u32 v55, vcc, 0, v55, vcc
	v_cmp_le_u32 vcc, v54, v186
	v_addc_co_u32 v55, vcc, 0, v55, vcc
	v_cmp_le_u32 vcc, v54, v185
	v_addc_co_u32 v55, vcc, 0, v55, vcc
	v_cmp_le_u32 vcc, v54, v184
	v_addc_co_u32 v55, vcc, 0, v55, vcc
	v_cmp_le_u32 vcc, v54, v183
	v_addc_co_u32 v55, vcc, 0, v55, vcc
	v_cmp_le_u32 vcc, v54, v182
	v_addc_co_u32 v55, vcc, 0, v55, vcc
	v_cmp_le_u32 vcc, v54, v181
	v_addc_co_u32 v55, vcc, 0, v55, vcc
	v_cmp_le_u32 vcc, v54, v180
	v_addc_co_u32 v55, vcc, 0, v55, vcc
	v_cmp_le_u32 vcc, v54, v179
	v_addc_co_u32 v55, vcc, 0, v55, vcc
	v_cmp_le_u32 vcc, v54, v178
	v_addc_co_u32 v55, vcc, 0, v55, vcc
	v_cmp_le_u32 vcc, v54, v177
	v_addc_co_u32 v55, vcc, 0, v55, vcc
	v_cmp_le_u32 vcc, v54, v176
	v_addc_co_u32 v55, vcc, 0, v55, vcc
	v_cmp_le_u32 vcc, v54, v175
	v_addc_co_u32 v55, vcc, 0, v55, vcc
	v_cmp_le_u32 vcc, v54, v173
	v_addc_co_u32 v55, vcc, 0, v55, vcc
	v_cmp_le_u32 vcc, v54, v174
	v_addc_co_u32 v55, vcc, 0, v55, vcc
	v_cmp_le_u32 vcc, v54, v172
	v_addc_co_u32 v55, vcc, 0, v55, vcc
	v_cmp_le_u32 vcc, v54, v171
	v_addc_co_u32 v55, vcc, 0, v55, vcc
	v_cmp_le_u32 vcc, v54, v170
	v_addc_co_u32 v55, vcc, 0, v55, vcc
	v_cmp_le_u32 vcc, v54, v169
	v_addc_co_u32 v55, vcc, 0, v55, vcc
	v_cmp_le_u32 vcc, v54, v168
	v_addc_co_u32 v55, vcc, 0, v55, vcc
	v_cmp_le_u32 vcc, v54, v167
	v_addc_co_u32 v55, vcc, 0, v55, vcc
	v_cmp_le_u32 vcc, v54, v166
	v_addc_co_u32 v55, vcc, 0, v55, vcc
	v_cmp_le_u32 vcc, v54, v165
	v_addc_co_u32 v55, vcc, 0, v55, vcc
	v_cmp_le_u32 vcc, v54, v164
; DI unsigned mbcnt64(unsigned long long m) { return __builtin_amdgcn_mbcnt_hi((unsigned)(m >> 32), __builtin_amdgcn_mbcnt_lo((unsigned)m, 0u)); }
; template <int NV>
; DI void topk_row(const float* row, int s, LAS int* lst, int lane) {
;     ...
; #pragma unroll 1
;     ...
;         const unsigned cand = T | (1u << bit); int c = 0;
; #pragma unroll
;         for (int j = 0; j < NV; ++j) asm volatile("v_cmp_le_u32 vcc, %2, %1\n\tv_addc_co_u32 %0, vcc, 0, %0, vcc" : "+v"(c) : "v"(key[j]), "s"(cand) : "vcc");
;         const int tot = wave_sum_i(c);
;         if (tot >= 256) T = cand;
;         if (tot == 256) break;
;     }
;     int bgt = 0;
; #pragma unroll
;     for (int j = 0; j < NV; ++j) { const bool sg = key[j] > T; const unsigned long long mg = __ballot(sg); if (sg) lst[bgt + (int)mbcnt64(mg)] = j * 64 + lane; bgt += __builtin_popcountll(mg); }
	v_addc_co_u32 v55, vcc, 0, v55, vcc
	v_cmp_le_u32 vcc, v54, v163
	v_addc_co_u32 v55, vcc, 0, v55, vcc
	v_cmp_le_u32 vcc, v54, v162
	v_addc_co_u32 v55, vcc, 0, v55, vcc
	v_cmp_le_u32 vcc, v54, v141
	v_addc_co_u32 v55, vcc, 0, v55, vcc
	v_cmp_le_u32 vcc, v54, v140
	v_addc_co_u32 v55, vcc, 0, v55, vcc
	v_cmp_le_u32 vcc, v54, v139
	v_addc_co_u32 v55, vcc, 0, v55, vcc
	v_cmp_le_u32 vcc, v54, v138
	v_addc_co_u32 v55, vcc, 0, v55, vcc
	v_cmp_le_u32 vcc, v54, v137
	v_addc_co_u32 v55, vcc, 0, v55, vcc
	v_cmp_le_u32 vcc, v54, v136
	v_addc_co_u32 v55, vcc, 0, v55, vcc
	v_cmp_le_u32 vcc, v54, v135
	v_addc_co_u32 v55, vcc, 0, v55, vcc
	v_cmp_le_u32 vcc, v54, v134
	v_addc_co_u32 v55, vcc, 0, v55, vcc
	v_cmp_le_u32 vcc, v54, v132
	v_addc_co_u32 v55, vcc, 0, v55, vcc
	v_cmp_le_u32 vcc, v54, v130
	v_addc_co_u32 v55, vcc, 0, v55, vcc
	v_cmp_le_u32 vcc, v54, v133
	v_addc_co_u32 v55, vcc, 0, v55, vcc
	v_cmp_le_u32 vcc, v54, v131
	v_addc_co_u32 v55, vcc, 0, v55, vcc
	v_cmp_le_u32 vcc, v54, v128
	v_addc_co_u32 v55, vcc, 0, v55, vcc
	v_cmp_le_u32 vcc, v54, v129
	v_addc_co_u32 v55, vcc, 0, v55, vcc
	v_cmp_le_u32 vcc, v54, v62
	v_addc_co_u32 v55, vcc, 0, v55, vcc
	v_cmp_le_u32 vcc, v54, v58
	v_addc_co_u32 v55, vcc, 0, v55, vcc
	v_cmp_le_u32 vcc, v54, v56
	v_addc_co_u32 v55, vcc, 0, v55, vcc
	v_cmp_le_u32 vcc, v54, v52
	v_addc_co_u32 v55, vcc, 0, v55, vcc
	v_cmp_le_u32 vcc, v54, v50
	v_addc_co_u32 v55, vcc, 0, v55, vcc
	v_cmp_le_u32 vcc, v54, v49
	v_addc_co_u32 v55, vcc, 0, v55, vcc
	v_cmp_le_u32 vcc, v54, v48
	v_addc_co_u32 v55, vcc, 0, v55, vcc
	v_cmp_le_u32 vcc, v54, v51
	v_addc_co_u32 v55, vcc, 0, v55, vcc
	v_cmp_le_u32 vcc, v54, v47
	v_addc_co_u32 v55, vcc, 0, v55, vcc
	v_cmp_le_u32 vcc, v54, v46
	v_addc_co_u32 v55, vcc, 0, v55, vcc
	v_cmp_le_u32 vcc, v54, v45
	v_addc_co_u32 v55, vcc, 0, v55, vcc
	v_cmp_le_u32 vcc, v54, v44
	v_addc_co_u32 v55, vcc, 0, v55, vcc
	v_cmp_le_u32 vcc, v54, v43
	v_addc_co_u32 v55, vcc, 0, v55, vcc
	v_cmp_le_u32 vcc, v54, v42
	v_addc_co_u32 v55, vcc, 0, v55, vcc
	v_cmp_le_u32 vcc, v54, v41
	v_addc_co_u32 v55, vcc, 0, v55, vcc
	v_cmp_le_u32 vcc, v54, v40
	v_addc_co_u32 v55, vcc, 0, v55, vcc
	v_cmp_le_u32 vcc, v54, v39
	v_addc_co_u32 v55, vcc, 0, v55, vcc
	v_cmp_le_u32 vcc, v54, v38
	v_addc_co_u32 v55, vcc, 0, v55, vcc
	v_cmp_le_u32 vcc, v54, v37
	v_addc_co_u32 v55, vcc, 0, v55, vcc
	v_cmp_le_u32 vcc, v54, v36
	v_addc_co_u32 v55, vcc, 0, v55, vcc
	v_cmp_le_u32 vcc, v54, v35
	v_addc_co_u32 v55, vcc, 0, v55, vcc
	v_cmp_le_u32 vcc, v54, v0
	v_addc_co_u32 v55, vcc, 0, v55, vcc
	s_nop 1
	v_add_u32_dpp v55, v55, v55 quad_perm:[1,0,3,2] row_mask:0xf bank_mask:0xf bound_ctrl:1
	s_nop 1
	v_add_u32_dpp v55, v55, v55 quad_perm:[2,3,0,1] row_mask:0xf bank_mask:0xf bound_ctrl:1
	s_nop 1
	v_add_u32_dpp v55, v55, v55 row_half_mirror row_mask:0xf bank_mask:0xf bound_ctrl:1
	s_nop 1
	v_add_u32_dpp v55, v55, v55 row_mirror row_mask:0xf bank_mask:0xf bound_ctrl:1
	s_nop 0
	v_readlane_b32 s0, v55, 0
	v_readlane_b32 s1, v55, 16
	s_add_i32 s0, s1, s0
	v_readlane_b32 s1, v55, 32
	s_add_i32 s0, s0, s1
	v_readlane_b32 s1, v55, 48
	s_add_i32 s0, s0, s1
	s_cmpk_gt_i32 s0, 0xff
	s_cselect_b64 vcc, -1, 0
	s_cmpk_eq_i32 s0, 0x100
	v_cndmask_b32_e32 v34, v34, v54, vcc
	s_cselect_b64 s[0:1], -1, 0
	v_subrev_co_u32_e32 v53, vcc, 1, v53
	s_or_b64 s[0:1], s[0:1], vcc
	s_andn2_b64 vcc, exec, s[0:1]
	s_cbranch_vccnz .LBB0_2485
	v_cmp_gt_u32_e32 vcc, v221, v34
	s_and_saveexec_b64 s[0:1], vcc
	s_nop 0
	v_mbcnt_lo_u32_b32 v53, vcc_lo, 0
	v_mbcnt_hi_u32_b32 v53, vcc_hi, v53
	v_lshl_add_u32 v53, v53, 2, s20
	ds_write_b32 v53, v2
	s_or_b64 exec, exec, s[0:1]
	s_bcnt1_i32_b64 s2, vcc
	v_cmp_gt_u32_e32 vcc, v220, v34
	s_and_saveexec_b64 s[0:1], vcc
	s_cbranch_execz .LBB0_2490
	s_lshl_b32 s3, s2, 2
	v_mbcnt_lo_u32_b32 v53, vcc_lo, 0
	s_add_i32 s3, s20, s3
	v_mbcnt_hi_u32_b32 v53, vcc_hi, v53
	v_lshl_add_u32 v53, v53, 2, s3
	ds_write_b32 v53, v4

; DI unsigned mbcnt64(unsigned long long m) { return __builtin_amdgcn_mbcnt_hi((unsigned)(m >> 32), __builtin_amdgcn_mbcnt_lo((unsigned)m, 0u)); }
; template <int NV>
; DI void topk_row(const float* row, int s, LAS int* lst, int lane) {
;     ...
; #pragma unroll 1
;     ...
;         const unsigned cand = T | (1u << bit); int c = 0;
; #pragma unroll
;         for (int j = 0; j < NV; ++j) asm volatile("v_cmp_le_u32 vcc, %2, %1\n\tv_addc_co_u32 %0, vcc, 0, %0, vcc" : "+v"(c) : "v"(key[j]), "s"(cand) : "vcc");
;         const int tot = wave_sum_i(c);
;         if (tot >= 256) T = cand;
;         if (tot == 256) break;
;     }
;     int bgt = 0;
; #pragma unroll
;     for (int j = 0; j < NV; ++j) { const bool sg = key[j] > T; const unsigned long long mg = __ballot(sg); if (sg) lst[bgt + (int)mbcnt64(mg)] = j * 64 + lane; bgt += __builtin_popcountll(mg); }
.LBB0_2871:
	v_lshlrev_b32_e64 v54, v53, 1
	v_mov_b32_e32 v55, 0
	v_or_b32_e32 v54, v54, v34
	v_cmp_le_u32 vcc, v54, v189
	v_addc_co_u32 v55, vcc, 0, v55, vcc
	v_cmp_le_u32 vcc, v54, v188
	v_addc_co_u32 v55, vcc, 0, v55, vcc
	v_cmp_le_u32 vcc, v54, v187
	v_addc_co_u32 v55, vcc, 0, v55, vcc
	v_cmp_le_u32 vcc, v54, v186
	v_addc_co_u32 v55, vcc, 0, v55, vcc
	v_cmp_le_u32 vcc, v54, v185
	v_addc_co_u32 v55, vcc, 0, v55, vcc
	v_cmp_le_u32 vcc, v54, v184
	v_addc_co_u32 v55, vcc, 0, v55, vcc
	v_cmp_le_u32 vcc, v54, v183
	v_addc_co_u32 v55, vcc, 0, v55, vcc
	v_cmp_le_u32 vcc, v54, v182
	v_addc_co_u32 v55, vcc, 0, v55, vcc
	v_cmp_le_u32 vcc, v54, v179
	v_addc_co_u32 v55, vcc, 0, v55, vcc
	v_cmp_le_u32 vcc, v54, v175
	v_addc_co_u32 v55, vcc, 0, v55, vcc
	v_cmp_le_u32 vcc, v54, v172
	v_addc_co_u32 v55, vcc, 0, v55, vcc
	v_cmp_le_u32 vcc, v54, v170
	v_addc_co_u32 v55, vcc, 0, v55, vcc
	v_cmp_le_u32 vcc, v54, v167
	v_addc_co_u32 v55, vcc, 0, v55, vcc
	v_cmp_le_u32 vcc, v54, v169
	v_addc_co_u32 v55, vcc, 0, v55, vcc
	v_cmp_le_u32 vcc, v54, v174
	v_addc_co_u32 v55, vcc, 0, v55, vcc
	v_cmp_le_u32 vcc, v54, v178
	v_addc_co_u32 v55, vcc, 0, v55, vcc
	v_cmp_le_u32 vcc, v54, v181
	v_addc_co_u32 v55, vcc, 0, v55, vcc
	v_cmp_le_u32 vcc, v54, v180
	v_addc_co_u32 v55, vcc, 0, v55, vcc
	v_cmp_le_u32 vcc, v54, v177
	v_addc_co_u32 v55, vcc, 0, v55, vcc
	v_cmp_le_u32 vcc, v54, v176
	v_addc_co_u32 v55, vcc, 0, v55, vcc
	v_cmp_le_u32 vcc, v54, v173
	v_addc_co_u32 v55, vcc, 0, v55, vcc
	v_cmp_le_u32 vcc, v54, v171
	v_addc_co_u32 v55, vcc, 0, v55, vcc
	v_cmp_le_u32 vcc, v54, v168
	v_addc_co_u32 v55, vcc, 0, v55, vcc
	v_cmp_le_u32 vcc, v54, v166
	v_addc_co_u32 v55, vcc, 0, v55, vcc
	v_cmp_le_u32 vcc, v54, v165
	v_addc_co_u32 v55, vcc, 0, v55, vcc
	v_cmp_le_u32 vcc, v54, v164
	v_addc_co_u32 v55, vcc, 0, v55, vcc
	v_cmp_le_u32 vcc, v54, v163
	v_addc_co_u32 v55, vcc, 0, v55, vcc
	v_cmp_le_u32 vcc, v54, v162
	v_addc_co_u32 v55, vcc, 0, v55, vcc
	v_cmp_le_u32 vcc, v54, v141
	v_addc_co_u32 v55, vcc, 0, v55, vcc
	v_cmp_le_u32 vcc, v54, v140
	v_addc_co_u32 v55, vcc, 0, v55, vcc
	v_cmp_le_u32 vcc, v54, v139
	v_addc_co_u32 v55, vcc, 0, v55, vcc
	v_cmp_le_u32 vcc, v54, v138
	v_addc_co_u32 v55, vcc, 0, v55, vcc
	v_cmp_le_u32 vcc, v54, v137
	v_addc_co_u32 v55, vcc, 0, v55, vcc
	v_cmp_le_u32 vcc, v54, v136
	v_addc_co_u32 v55, vcc, 0, v55, vcc
	v_cmp_le_u32 vcc, v54, v135
	v_addc_co_u32 v55, vcc, 0, v55, vcc
	v_cmp_le_u32 vcc, v54, v134
	v_addc_co_u32 v55, vcc, 0, v55, vcc
	v_cmp_le_u32 vcc, v54, v133
	v_addc_co_u32 v55, vcc, 0, v55, vcc
	v_cmp_le_u32 vcc, v54, v131
	v_addc_co_u32 v55, vcc, 0, v55, vcc
	v_cmp_le_u32 vcc, v54, v132
	v_addc_co_u32 v55, vcc, 0, v55, vcc
	v_cmp_le_u32 vcc, v54, v130
	v_addc_co_u32 v55, vcc, 0, v55, vcc
	v_cmp_le_u32 vcc, v54, v128
	v_addc_co_u32 v55, vcc, 0, v55, vcc
	v_cmp_le_u32 vcc, v54, v129
	v_addc_co_u32 v55, vcc, 0, v55, vcc
	v_cmp_le_u32 vcc, v54, v62
	v_addc_co_u32 v55, vcc, 0, v55, vcc
	v_cmp_le_u32 vcc, v54, v58
	v_addc_co_u32 v55, vcc, 0, v55, vcc
	v_cmp_le_u32 vcc, v54, v56
	v_addc_co_u32 v55, vcc, 0, v55, vcc
	v_cmp_le_u32 vcc, v54, v52
	v_addc_co_u32 v55, vcc, 0, v55, vcc
	v_cmp_le_u32 vcc, v54, v50
	v_addc_co_u32 v55, vcc, 0, v55, vcc
	v_cmp_le_u32 vcc, v54, v49
	v_addc_co_u32 v55, vcc, 0, v55, vcc
	v_cmp_le_u32 vcc, v54, v48
	v_addc_co_u32 v55, vcc, 0, v55, vcc
	v_cmp_le_u32 vcc, v54, v51
	v_addc_co_u32 v55, vcc, 0, v55, vcc
	v_cmp_le_u32 vcc, v54, v47
	v_addc_co_u32 v55, vcc, 0, v55, vcc
	v_cmp_le_u32 vcc, v54, v46
	v_addc_co_u32 v55, vcc, 0, v55, vcc
	v_cmp_le_u32 vcc, v54, v45
	v_addc_co_u32 v55, vcc, 0, v55, vcc
	v_cmp_le_u32 vcc, v54, v44
	v_addc_co_u32 v55, vcc, 0, v55, vcc
	v_cmp_le_u32 vcc, v54, v43
	v_addc_co_u32 v55, vcc, 0, v55, vcc
	v_cmp_le_u32 vcc, v54, v42
	v_addc_co_u32 v55, vcc, 0, v55, vcc
	v_cmp_le_u32 vcc, v54, v41
	v_addc_co_u32 v55, vcc, 0, v55, vcc
	v_cmp_le_u32 vcc, v54, v40
	v_addc_co_u32 v55, vcc, 0, v55, vcc
	v_cmp_le_u32 vcc, v54, v39
	v_addc_co_u32 v55, vcc, 0, v55, vcc
	v_cmp_le_u32 vcc, v54, v38
	v_addc_co_u32 v55, vcc, 0, v55, vcc
	v_cmp_le_u32 vcc, v54, v37
	v_addc_co_u32 v55, vcc, 0, v55, vcc
	v_cmp_le_u32 vcc, v54, v36
	v_addc_co_u32 v55, vcc, 0, v55, vcc
	v_cmp_le_u32 vcc, v54, v35
	v_addc_co_u32 v55, vcc, 0, v55, vcc
	v_cmp_le_u32 vcc, v54, v0
	v_addc_co_u32 v55, vcc, 0, v55, vcc
	s_nop 1
	v_add_u32_dpp v55, v55, v55 quad_perm:[1,0,3,2] row_mask:0xf bank_mask:0xf bound_ctrl:1
	s_nop 1
	v_add_u32_dpp v55, v55, v55 quad_perm:[2,3,0,1] row_mask:0xf bank_mask:0xf bound_ctrl:1
	s_nop 1
	v_add_u32_dpp v55, v55, v55 row_half_mirror row_mask:0xf bank_mask:0xf bound_ctrl:1
	s_nop 1
	v_add_u32_dpp v55, v55, v55 row_mirror row_mask:0xf bank_mask:0xf bound_ctrl:1
	s_nop 0
	v_readlane_b32 s0, v55, 0
	v_readlane_b32 s1, v55, 16
	s_add_i32 s0, s1, s0
	v_readlane_b32 s1, v55, 32
	s_add_i32 s0, s0, s1
	v_readlane_b32 s1, v55, 48
	s_add_i32 s0, s0, s1
	s_cmpk_gt_i32 s0, 0xff
	s_cselect_b64 vcc, -1, 0
	s_cmpk_eq_i32 s0, 0x100
	v_cndmask_b32_e32 v34, v34, v54, vcc
	s_cselect_b64 s[0:1], -1, 0
	v_subrev_co_u32_e32 v53, vcc, 1, v53
	s_or_b64 s[0:1], s[0:1], vcc
	s_andn2_b64 vcc, exec, s[0:1]
	s_cbranch_vccnz .LBB0_2871
	v_cmp_gt_u32_e32 vcc, v189, v34
	s_and_saveexec_b64 s[0:1], vcc
	s_nop 0
	v_mbcnt_lo_u32_b32 v53, vcc_lo, 0
	v_mbcnt_hi_u32_b32 v53, vcc_hi, v53
	v_lshl_add_u32 v53, v53, 2, s20
	ds_write_b32 v53, v2
	s_or_b64 exec, exec, s[0:1]
	s_bcnt1_i32_b64 s2, vcc
	v_cmp_gt_u32_e32 vcc, v188, v34
	s_and_saveexec_b64 s[0:1], vcc
	s_cbranch_execz .LBB0_2876
	s_lshl_b32 s3, s2, 2
	v_mbcnt_lo_u32_b32 v53, vcc_lo, 0
	s_add_i32 s3, s20, s3
	v_mbcnt_hi_u32_b32 v53, vcc_hi, v53
	v_lshl_add_u32 v53, v53, 2, s3
	ds_write_b32 v53, v4

; DI unsigned mbcnt64(unsigned long long m) { return __builtin_amdgcn_mbcnt_hi((unsigned)(m >> 32), __builtin_amdgcn_mbcnt_lo((unsigned)m, 0u)); }
; template <int NV>
; DI void topk_row(const float* row, int s, LAS int* lst, int lane) {
;     ...
; #pragma unroll 1
;     ...
;         const unsigned cand = T | (1u << bit); int c = 0;
; #pragma unroll
;         for (int j = 0; j < NV; ++j) asm volatile("v_cmp_le_u32 vcc, %2, %1\n\tv_addc_co_u32 %0, vcc, 0, %0, vcc" : "+v"(c) : "v"(key[j]), "s"(cand) : "vcc");
;         const int tot = wave_sum_i(c);
;         if (tot >= 256) T = cand;
;         if (tot == 256) break;
;     }
;     int bgt = 0;
; #pragma unroll
;     for (int j = 0; j < NV; ++j) { const bool sg = key[j] > T; const unsigned long long mg = __ballot(sg); if (sg) lst[bgt + (int)mbcnt64(mg)] = j * 64 + lane; bgt += __builtin_popcountll(mg); }
.LBB0_3129:
	v_lshlrev_b32_e64 v131, v130, 1
	v_mov_b32_e32 v132, 0
	v_or_b32_e32 v131, v131, v129
	v_cmp_le_u32 vcc, v131, v44
	v_addc_co_u32 v132, vcc, 0, v132, vcc
	v_cmp_le_u32 vcc, v131, v43
	v_addc_co_u32 v132, vcc, 0, v132, vcc
	v_cmp_le_u32 vcc, v131, v42
	v_addc_co_u32 v132, vcc, 0, v132, vcc
	v_cmp_le_u32 vcc, v131, v41
	v_addc_co_u32 v132, vcc, 0, v132, vcc
	v_cmp_le_u32 vcc, v131, v40
	v_addc_co_u32 v132, vcc, 0, v132, vcc
	v_cmp_le_u32 vcc, v131, v39
	v_addc_co_u32 v132, vcc, 0, v132, vcc
	v_cmp_le_u32 vcc, v131, v38
	v_addc_co_u32 v132, vcc, 0, v132, vcc
	v_cmp_le_u32 vcc, v131, v37
	v_addc_co_u32 v132, vcc, 0, v132, vcc
	v_cmp_le_u32 vcc, v131, v36
	v_addc_co_u32 v132, vcc, 0, v132, vcc
	v_cmp_le_u32 vcc, v131, v35
	v_addc_co_u32 v132, vcc, 0, v132, vcc
	v_cmp_le_u32 vcc, v131, v34
	v_addc_co_u32 v132, vcc, 0, v132, vcc
	v_cmp_le_u32 vcc, v131, v45
	v_addc_co_u32 v132, vcc, 0, v132, vcc
	v_cmp_le_u32 vcc, v131, v46
	v_addc_co_u32 v132, vcc, 0, v132, vcc
	v_cmp_le_u32 vcc, v131, v47
	v_addc_co_u32 v132, vcc, 0, v132, vcc
	v_cmp_le_u32 vcc, v131, v48
	v_addc_co_u32 v132, vcc, 0, v132, vcc
	v_cmp_le_u32 vcc, v131, v51
	v_addc_co_u32 v132, vcc, 0, v132, vcc
	v_cmp_le_u32 vcc, v131, v57
	v_addc_co_u32 v132, vcc, 0, v132, vcc
	v_cmp_le_u32 vcc, v131, v63
	v_addc_co_u32 v132, vcc, 0, v132, vcc
	v_cmp_le_u32 vcc, v131, v62
	v_addc_co_u32 v132, vcc, 0, v132, vcc
	v_cmp_le_u32 vcc, v131, v61
	v_addc_co_u32 v132, vcc, 0, v132, vcc
	v_cmp_le_u32 vcc, v131, v60
	v_addc_co_u32 v132, vcc, 0, v132, vcc
	v_cmp_le_u32 vcc, v131, v59
	v_addc_co_u32 v132, vcc, 0, v132, vcc
	v_cmp_le_u32 vcc, v131, v58
	v_addc_co_u32 v132, vcc, 0, v132, vcc
	v_cmp_le_u32 vcc, v131, v56
	v_addc_co_u32 v132, vcc, 0, v132, vcc
	v_cmp_le_u32 vcc, v131, v55
	v_addc_co_u32 v132, vcc, 0, v132, vcc
	v_cmp_le_u32 vcc, v131, v54
	v_addc_co_u32 v132, vcc, 0, v132, vcc
	v_cmp_le_u32 vcc, v131, v53
	v_addc_co_u32 v132, vcc, 0, v132, vcc
	v_cmp_le_u32 vcc, v131, v52
	v_addc_co_u32 v132, vcc, 0, v132, vcc
	v_cmp_le_u32 vcc, v131, v50
	v_addc_co_u32 v132, vcc, 0, v132, vcc
	v_cmp_le_u32 vcc, v131, v49
	v_addc_co_u32 v132, vcc, 0, v132, vcc
	v_cmp_le_u32 vcc, v131, v0
	v_addc_co_u32 v132, vcc, 0, v132, vcc
	v_cmp_le_u32 vcc, v131, v128
	v_addc_co_u32 v132, vcc, 0, v132, vcc
	s_nop 1
	v_add_u32_dpp v132, v132, v132 quad_perm:[1,0,3,2] row_mask:0xf bank_mask:0xf bound_ctrl:1
	s_nop 1
	v_add_u32_dpp v132, v132, v132 quad_perm:[2,3,0,1] row_mask:0xf bank_mask:0xf bound_ctrl:1
	s_nop 1
	v_add_u32_dpp v132, v132, v132 row_half_mirror row_mask:0xf bank_mask:0xf bound_ctrl:1
	s_nop 1
	v_add_u32_dpp v132, v132, v132 row_mirror row_mask:0xf bank_mask:0xf bound_ctrl:1
	s_nop 0
	v_readlane_b32 s0, v132, 0
	v_readlane_b32 s1, v132, 16
	s_add_i32 s0, s1, s0
	v_readlane_b32 s1, v132, 32
	s_add_i32 s0, s0, s1
	v_readlane_b32 s1, v132, 48
	s_add_i32 s0, s0, s1
	s_cmpk_gt_i32 s0, 0xff
	s_cselect_b64 vcc, -1, 0
	s_cmpk_eq_i32 s0, 0x100
	v_cndmask_b32_e32 v129, v129, v131, vcc
	s_cselect_b64 s[0:1], -1, 0
	v_subrev_co_u32_e32 v130, vcc, 1, v130
	s_or_b64 s[0:1], s[0:1], vcc
	s_andn2_b64 vcc, exec, s[0:1]
	s_cbranch_vccnz .LBB0_3129
	v_cmp_gt_u32_e32 vcc, v44, v129
	s_and_saveexec_b64 s[0:1], vcc
	s_nop 0
	v_mbcnt_lo_u32_b32 v130, vcc_lo, 0
	v_mbcnt_hi_u32_b32 v130, vcc_hi, v130
	v_lshl_add_u32 v130, v130, 2, s20
	ds_write_b32 v130, v2
	s_or_b64 exec, exec, s[0:1]
	s_bcnt1_i32_b64 s2, vcc
	v_cmp_gt_u32_e32 vcc, v43, v129
	s_and_saveexec_b64 s[0:1], vcc
	s_cbranch_execz .LBB0_3134
	s_lshl_b32 s3, s2, 2
	v_mbcnt_lo_u32_b32 v130, vcc_lo, 0
	s_add_i32 s3, s20, s3
	v_mbcnt_hi_u32_b32 v130, vcc_hi, v130
	v_lshl_add_u32 v130, v130, 2, s3
	ds_write_b32 v130, v4
